# first K-iteration of the three int8 GEMM loops peeled with C = 0, the 128 accumulator zeroing moves per tile deleted (on top of static priority for waves 0-3)
# speedup vs baseline: 1.0089x; 1.0022x over previous
;     static __device__ __forceinline__ size_t a_off(const Gemm& g, const Unit& u) { return (size_t)u.pm * 256 * g.lda * 2; }
;     static __device__ __forceinline__ size_t b_off(const Gemm& g, const Unit& u) { return (size_t)u.pn * 256 * g.ldb * 2; }
;     static __device__ __forceinline__ size_t a_off(const Gemm& g, const Unit& u) { return ((size_t)u.pm * 256 * g.lda + (size_t)(u.pn >> 1) * 256) * 2; }
;     static __device__ __forceinline__ size_t b_off(const Gemm& g, const Unit& u) { return (size_t)u.pn * 256 * g.ldb * 2; }
;     __host__ __device__ bool next(int i, Unit& u) const { const long L = (long)i * G + c; if (L >= limit) return false; tile_of((int)L, u); return true; }
;     __host__ __device__ bool next(int i, Unit& u) const { if (i > 0 || c >= nrem * 8) return false; base.tile_of(first + c % nrem, u); u.tl = c % nrem; u.ks = c / nrem; return true; }
;     static __device__ __forceinline__ size_t a_off(const Gemm& g, const Unit& u) { return ((size_t)u.pm * 256 * g.lda + (size_t)u.ks * g.K) * 2; }
;     static __device__ __forceinline__ size_t b_off(const Gemm& g, const Unit& u) { return ((size_t)u.pn * 256 * g.ldb + (size_t)u.ks * g.K) * 2; }
; template <class Epi, class Geom, class Sched, bool ALIGN_EPI, bool I8 = false>
; __device__ __forceinline__ void gemm_phase(LAS unsigned char* lds, const Gemm g, const Sched& S, const Epi& E) {
;     ...
;     for (;;) {
;         const bool has_next = S.next(ui + 1, nxt);
;         const char* nA = has_next ? (const char*)g.A + Geom::a_off(g, nxt) : cA; const char* nB = has_next ? (const char*)g.Bt + Geom::b_off(g, nxt) : cB;
; #pragma unroll 1
;         for (int t = 0; t < nt; t += 2) {
;             const bool last = (t == nt - 2);
;             const char* a1 = cA + (size_t)(t + 1) * kstep;
;             const char* a2 = last ? nA : cA + (size_t)(t + 2) * kstep; const char* b2 = last ? nB : cB + (size_t)(t + 2) * kstep;
;             const char* a3 = a2 + kstep; const char* b3 = b2 + kstep;
.LBB0_2230:
	s_ashr_i32 s23, s22, 31
	s_lshl_b64 s[24:25], s[22:23], 20
	s_add_u32 s24, s33, s24
	s_addc_u32 s25, s38, s25
	s_and_b64 s[26:27], s[4:5], exec
	s_cselect_b32 s23, s25, s31
	s_cselect_b32 s57, s24, s30
	s_ashr_i32 s21, s20, 31
	s_lshl_b64 s[26:27], s[20:21], 20
	s_add_u32 s26, s39, s26
	s_addc_u32 s27, s40, s27
	s_and_b64 s[36:37], s[4:5], exec
	s_cselect_b32 s21, s27, s35
	s_cselect_b32 s58, s26, s34
	s_add_u32 s30, s30, 0x80080
	s_addc_u32 s31, s31, 0
	s_add_u32 s59, s34, 0x100
	s_addc_u32 s60, s35, 0
	s_mov_b32 s61, -2
	s_branch .Lpz1_0

; #define PG8_STAGE(bufoff, gbase, voff) do { _Pragma("unroll") for (int _i = 0; _i < 2; ++_i) \
;         __builtin_amdgcn_global_load_lds((const unsigned*)((const char*)(gbase) + (voff)[_i]), (LAS unsigned*)(lds + (bufoff) + ldsw + _i * 8192), 16, 0, 0); } while (0)
; #define PG8_LDA(dst, b, h) do { _Pragma("unroll") for (int m = 0; m < 4; ++m) _Pragma("unroll") for (int k = 0; k < 2; ++k) dst[m][k] = *(const LAS bf16x8*)(lds + PG8_SA(b, h) + aoff + m * 2048 + k * 1024); } while (0)
; #define PG8_LDB(dst, b, h) do { _Pragma("unroll") for (int n = 0; n < 2; ++n) _Pragma("unroll") for (int k = 0; k < 2; ++k) dst[n][k] = *(const LAS bf16x8*)(lds + PG8_SB(b, h) + boff + n * 2048 + k * 1024); } while (0)
; #define PG8_WAIT_V(n) asm volatile("s_waitcnt vmcnt(" #n ")" ::: "memory")
; #define PG8_WAIT_L(n) asm volatile("s_waitcnt lgkmcnt(" #n ")" ::: "memory")
; #define PG8_BAR __builtin_amdgcn_s_barrier()
; #define PG8_SCHED __builtin_amdgcn_sched_barrier(0)
; template <class Epi, class Geom, class Sched, bool ALIGN_EPI, bool I8 = false>
; __device__ __forceinline__ void gemm_phase(LAS unsigned char* lds, const Gemm g, const Sched& S, const Epi& E) {
;     ...
;             PG8_LDB(B0, 0, 0); PG8_LDB(B1, 0, 1); PG8_SCHED; PG8_LDA(At, 0, 0); PG8_STAGE(PG8_SA(1, 1), a1 + hsA, voffA);
;             PG8_WAIT_V(8); PG8_WAIT_L(0); PG8_BAR; PG8_MMA(0, 0, At, B0); PG8_MMA(0, 1, At, B1); PG8_BAR; PG8_SCHED;
;             PG8_LDA(At, 0, 1); PG8_STAGE(PG8_SB(0, 0), b2, voffB); PG8_STAGE(PG8_SB(0, 1), b2 + hsB, voffB); PG8_STAGE(PG8_SA(0, 0), a2, voffA);
;             PG8_WAIT_V(8); PG8_WAIT_L(0); PG8_BAR; PG8_MMA(1, 0, At, B0); PG8_MMA(1, 1, At, B1); PG8_BAR; PG8_SCHED;
.Lpz1_0:
	ds_read_b128 v[102:105], v166
	ds_read_b128 v[106:109], v166 offset:1024
	ds_read_b128 v[114:117], v166 offset:2048
	ds_read_b128 v[118:121], v166 offset:3072
	ds_read_b128 v[156:159], v167
	ds_read_b128 v[170:173], v167 offset:1024
	ds_read_b128 v[174:177], v167 offset:2048
	ds_read_b128 v[178:181], v167 offset:3072
	s_add_u32 s34, s30, 0xfff80080
	s_addc_u32 s35, s31, -1
	s_cmp_eq_u32 s61, 28
	s_cselect_b32 s37, s23, s35
	s_cselect_b32 s36, s57, s34
	s_cselect_b32 s35, s21, s60
	s_cselect_b32 s34, s58, s59
	v_lshl_add_u64 v[160:161], s[30:31], 0, v[150:151]
	s_add_i32 m0, s29, 0xc000
	ds_read_b128 v[182:185], v168
	ds_read_b128 v[186:189], v168 offset:1024
	ds_read_b128 v[190:193], v168 offset:2048
	ds_read_b128 v[194:197], v168 offset:3072
	ds_read_b128 v[198:201], v168 offset:4096
	ds_read_b128 v[202:205], v168 offset:5120
	ds_read_b128 v[206:209], v168 offset:6144
	ds_read_b128 v[210:213], v168 offset:7168
	global_load_lds_dwordx4 v[160:161], off
	v_lshl_add_u64 v[160:161], s[30:31], 0, v[152:153]
	s_add_i32 m0, s29, 0xe000
	s_nop 0
	global_load_lds_dwordx4 v[160:161], off
	s_waitcnt vmcnt(8)
	s_waitcnt lgkmcnt(0)
	s_barrier
	s_waitcnt lgkmcnt(0)
	v_mfma_i32_16x16x64_i8 v[142:145], v[102:105], v[182:185], 0
	v_mfma_i32_16x16x64_i8 v[138:141], v[114:117], v[182:185], 0
	v_mfma_i32_16x16x64_i8 v[126:129], v[102:105], v[190:193], 0
	v_mfma_i32_16x16x64_i8 v[122:125], v[114:117], v[190:193], 0
	v_mfma_i32_16x16x64_i8 v[94:97], v[102:105], v[198:201], 0
	v_mfma_i32_16x16x64_i8 v[90:93], v[114:117], v[198:201], 0
	v_mfma_i32_16x16x64_i8 v[82:85], v[102:105], v[206:209], 0
	v_mfma_i32_16x16x64_i8 v[74:77], v[114:117], v[206:209], 0
	v_mfma_i32_16x16x64_i8 v[142:145], v[106:109], v[186:189], v[142:145]
	v_mfma_i32_16x16x64_i8 v[138:141], v[118:121], v[186:189], v[138:141]
	v_mfma_i32_16x16x64_i8 v[126:129], v[106:109], v[194:197], v[126:129]
	v_mfma_i32_16x16x64_i8 v[122:125], v[118:121], v[194:197], v[122:125]
	v_mfma_i32_16x16x64_i8 v[94:97], v[106:109], v[202:205], v[94:97]
	v_mfma_i32_16x16x64_i8 v[90:93], v[118:121], v[202:205], v[90:93]
	v_mfma_i32_16x16x64_i8 v[82:85], v[106:109], v[210:213], v[82:85]
	v_mfma_i32_16x16x64_i8 v[74:77], v[118:121], v[210:213], v[74:77]
	v_mfma_i32_16x16x64_i8 v[134:137], v[156:159], v[182:185], 0
	v_mfma_i32_16x16x64_i8 v[130:133], v[174:177], v[182:185], 0
	v_mfma_i32_16x16x64_i8 v[110:113], v[156:159], v[190:193], 0
	v_mfma_i32_16x16x64_i8 v[98:101], v[174:177], v[190:193], 0
	v_mfma_i32_16x16x64_i8 v[86:89], v[156:159], v[198:201], 0
	v_mfma_i32_16x16x64_i8 v[78:81], v[174:177], v[198:201], 0
	v_mfma_i32_16x16x64_i8 v[70:73], v[156:159], v[206:209], 0
	v_mfma_i32_16x16x64_i8 v[66:69], v[174:177], v[206:209], 0
	v_mfma_i32_16x16x64_i8 v[134:137], v[170:173], v[186:189], v[134:137]
	v_mfma_i32_16x16x64_i8 v[130:133], v[178:181], v[186:189], v[130:133]
	v_mfma_i32_16x16x64_i8 v[110:113], v[170:173], v[194:197], v[110:113]
	v_mfma_i32_16x16x64_i8 v[98:101], v[178:181], v[194:197], v[98:101]
	v_mfma_i32_16x16x64_i8 v[86:89], v[170:173], v[202:205], v[86:89]
	v_mfma_i32_16x16x64_i8 v[78:81], v[178:181], v[202:205], v[78:81]
	v_mfma_i32_16x16x64_i8 v[70:73], v[170:173], v[210:213], v[70:73]
	v_mfma_i32_16x16x64_i8 v[66:69], v[178:181], v[210:213], v[66:69]
	s_barrier
	s_add_i32 s62, s10, s41
	v_lshl_add_u64 v[160:161], s[34:35], 0, v[146:147]
	s_mov_b32 m0, s62
	ds_read_b128 v[182:185], v168 offset:16384
	ds_read_b128 v[186:189], v168 offset:17408
	ds_read_b128 v[190:193], v168 offset:18432
	ds_read_b128 v[194:197], v168 offset:19456
	ds_read_b128 v[198:201], v168 offset:20480
	ds_read_b128 v[202:205], v168 offset:21504
	ds_read_b128 v[206:209], v168 offset:22528
	ds_read_b128 v[210:213], v168 offset:23552
	global_load_lds_dwordx4 v[160:161], off
	s_add_i32 m0, s62, 0x2000
	s_add_u32 s62, s34, 0x80000
	v_lshl_add_u64 v[214:215], s[34:35], 0, v[148:149]
	s_addc_u32 s63, s35, 0
	s_add_i32 s64, s50, s41
	global_load_lds_dwordx4 v[214:215], off
	v_lshl_add_u64 v[216:217], s[62:63], 0, v[146:147]
	s_mov_b32 m0, s64
	v_lshl_add_u64 v[218:219], s[36:37], 0, v[148:149]
	global_load_lds_dwordx4 v[216:217], off
	v_lshl_add_u64 v[216:217], s[62:63], 0, v[148:149]
	s_add_i32 m0, s64, 0x2000
	s_nop 0
	global_load_lds_dwordx4 v[216:217], off
	v_lshl_add_u64 v[216:217], s[36:37], 0, v[146:147]
	s_mov_b32 m0, s29
	s_nop 0
	global_load_lds_dwordx4 v[216:217], off
	s_mov_b32 m0, s44
	s_nop 0
	global_load_lds_dwordx4 v[218:219], off
	s_waitcnt vmcnt(8)
	s_waitcnt lgkmcnt(0)
	s_barrier
	s_waitcnt lgkmcnt(0)
	v_mfma_i32_16x16x64_i8 v[62:65], v[102:105], v[182:185], 0
	v_mfma_i32_16x16x64_i8 v[58:61], v[114:117], v[182:185], 0
	v_mfma_i32_16x16x64_i8 v[50:53], v[102:105], v[190:193], 0
	v_mfma_i32_16x16x64_i8 v[42:45], v[114:117], v[190:193], 0
	v_mfma_i32_16x16x64_i8 v[30:33], v[102:105], v[198:201], 0
	v_mfma_i32_16x16x64_i8 v[26:29], v[114:117], v[198:201], 0
	v_mfma_i32_16x16x64_i8 v[18:21], v[102:105], v[206:209], 0
	v_mfma_i32_16x16x64_i8 v[10:13], v[114:117], v[206:209], 0
	v_mfma_i32_16x16x64_i8 v[62:65], v[106:109], v[186:189], v[62:65]
	v_mfma_i32_16x16x64_i8 v[58:61], v[118:121], v[186:189], v[58:61]
	v_mfma_i32_16x16x64_i8 v[50:53], v[106:109], v[194:197], v[50:53]
	v_mfma_i32_16x16x64_i8 v[42:45], v[118:121], v[194:197], v[42:45]
	v_mfma_i32_16x16x64_i8 v[30:33], v[106:109], v[202:205], v[30:33]
	v_mfma_i32_16x16x64_i8 v[26:29], v[118:121], v[202:205], v[26:29]
	v_mfma_i32_16x16x64_i8 v[18:21], v[106:109], v[210:213], v[18:21]
	v_mfma_i32_16x16x64_i8 v[10:13], v[118:121], v[210:213], v[10:13]
	v_mfma_i32_16x16x64_i8 v[54:57], v[156:159], v[182:185], 0
	v_mfma_i32_16x16x64_i8 v[46:49], v[174:177], v[182:185], 0
	v_mfma_i32_16x16x64_i8 v[38:41], v[156:159], v[190:193], 0
	v_mfma_i32_16x16x64_i8 v[34:37], v[174:177], v[190:193], 0
	v_mfma_i32_16x16x64_i8 v[22:25], v[156:159], v[198:201], 0
	v_mfma_i32_16x16x64_i8 v[14:17], v[174:177], v[198:201], 0
	v_mfma_i32_16x16x64_i8 v[6:9], v[156:159], v[206:209], 0
	v_mfma_i32_16x16x64_i8 v[2:5], v[174:177], v[206:209], 0
	v_mfma_i32_16x16x64_i8 v[54:57], v[170:173], v[186:189], v[54:57]
	v_mfma_i32_16x16x64_i8 v[46:49], v[178:181], v[186:189], v[46:49]
	v_mfma_i32_16x16x64_i8 v[38:41], v[170:173], v[194:197], v[38:41]
	v_mfma_i32_16x16x64_i8 v[34:37], v[178:181], v[194:197], v[34:37]
	v_mfma_i32_16x16x64_i8 v[22:25], v[170:173], v[202:205], v[22:25]
	v_mfma_i32_16x16x64_i8 v[14:17], v[178:181], v[202:205], v[14:17]
	v_mfma_i32_16x16x64_i8 v[6:9], v[170:173], v[210:213], v[6:9]
	v_mfma_i32_16x16x64_i8 v[2:5], v[178:181], v[210:213], v[2:5]
	s_barrier
; #define PG8_STAGE(bufoff, gbase, voff) do { _Pragma("unroll") for (int _i = 0; _i < 2; ++_i) \
;         __builtin_amdgcn_global_load_lds((const unsigned*)((const char*)(gbase) + (voff)[_i]), (LAS unsigned*)(lds + (bufoff) + ldsw + _i * 8192), 16, 0, 0); } while (0)
; #define PG8_LDA(dst, b, h) do { _Pragma("unroll") for (int m = 0; m < 4; ++m) _Pragma("unroll") for (int k = 0; k < 2; ++k) dst[m][k] = *(const LAS bf16x8*)(lds + PG8_SA(b, h) + aoff + m * 2048 + k * 1024); } while (0)
; #define PG8_LDB(dst, b, h) do { _Pragma("unroll") for (int n = 0; n < 2; ++n) _Pragma("unroll") for (int k = 0; k < 2; ++k) dst[n][k] = *(const LAS bf16x8*)(lds + PG8_SB(b, h) + boff + n * 2048 + k * 1024); } while (0)
; #define PG8_WAIT_V(n) asm volatile("s_waitcnt vmcnt(" #n ")" ::: "memory")
; #define PG8_WAIT_L(n) asm volatile("s_waitcnt lgkmcnt(" #n ")" ::: "memory")
; #define PG8_BAR __builtin_amdgcn_s_barrier()
; #define PG8_SCHED __builtin_amdgcn_sched_barrier(0)
; template <class Epi, class Geom, class Sched, bool ALIGN_EPI, bool I8 = false>
; __device__ __forceinline__ void gemm_phase(LAS unsigned char* lds, const Gemm g, const Sched& S, const Epi& E) {
;     ...
;             PG8_LDB(B0, 1, 0); PG8_LDB(B1, 1, 1); PG8_SCHED; PG8_LDA(At, 1, 0); PG8_STAGE(PG8_SA(0, 1), a2 + hsA, voffA);
;             PG8_WAIT_V(8); PG8_WAIT_L(0); PG8_BAR; PG8_MMA(0, 0, At, B0); PG8_MMA(0, 1, At, B1); PG8_BAR; PG8_SCHED;
;             PG8_LDA(At, 1, 1); PG8_STAGE(PG8_SB(1, 0), b3, voffB); PG8_STAGE(PG8_SB(1, 1), b3 + hsB, voffB); PG8_STAGE(PG8_SA(1, 0), a3, voffA);
;             PG8_WAIT_V(8); PG8_WAIT_L(0); PG8_BAR; PG8_MMA(1, 0, At, B0); PG8_MMA(1, 1, At, B1); PG8_BAR; PG8_SCHED;
;         }
	s_add_i32 s62, 0, 0x18000
	s_add_i32 s63, 0, 0x1c000
	v_add_u32_e32 v118, s62, v164
	v_add_u32_e32 v162, s63, v164
	ds_read_b128 v[102:105], v118
	ds_read_b128 v[106:109], v118 offset:1024
	ds_read_b128 v[114:117], v118 offset:2048
	ds_read_b128 v[118:121], v118 offset:3072
	ds_read_b128 v[156:159], v162
	ds_read_b128 v[170:173], v162 offset:1024
	ds_read_b128 v[174:177], v162 offset:2048
	ds_read_b128 v[178:181], v162 offset:3072
	s_add_u32 s36, s36, 0x80000
	s_addc_u32 s37, s37, 0
	s_mov_b32 m0, s45
	v_lshl_add_u64 v[220:221], s[36:37], 0, v[146:147]
	ds_read_b128 v[182:185], v168 offset:32768
	ds_read_b128 v[186:189], v168 offset:33792
	ds_read_b128 v[190:193], v168 offset:34816
	ds_read_b128 v[194:197], v168 offset:35840
	ds_read_b128 v[198:201], v168 offset:36864
	ds_read_b128 v[202:205], v168 offset:37888
	ds_read_b128 v[206:209], v168 offset:38912
	ds_read_b128 v[210:213], v168 offset:39936
	global_load_lds_dwordx4 v[220:221], off
	v_lshl_add_u64 v[220:221], s[36:37], 0, v[148:149]
	s_mov_b32 m0, s46
	s_nop 0
	global_load_lds_dwordx4 v[220:221], off
	s_waitcnt vmcnt(8)
	s_waitcnt lgkmcnt(0)
	s_barrier
	s_waitcnt lgkmcnt(0)
	v_mfma_i32_16x16x64_i8 v[142:145], v[102:105], v[182:185], v[142:145]
	v_mfma_i32_16x16x64_i8 v[138:141], v[114:117], v[182:185], v[138:141]
	v_mfma_i32_16x16x64_i8 v[126:129], v[102:105], v[190:193], v[126:129]
	v_mfma_i32_16x16x64_i8 v[122:125], v[114:117], v[190:193], v[122:125]
	v_mfma_i32_16x16x64_i8 v[94:97], v[102:105], v[198:201], v[94:97]
	v_mfma_i32_16x16x64_i8 v[90:93], v[114:117], v[198:201], v[90:93]
	v_mfma_i32_16x16x64_i8 v[82:85], v[102:105], v[206:209], v[82:85]
	v_mfma_i32_16x16x64_i8 v[74:77], v[114:117], v[206:209], v[74:77]
	v_mfma_i32_16x16x64_i8 v[142:145], v[106:109], v[186:189], v[142:145]
	v_mfma_i32_16x16x64_i8 v[138:141], v[118:121], v[186:189], v[138:141]
	v_mfma_i32_16x16x64_i8 v[126:129], v[106:109], v[194:197], v[126:129]
	v_mfma_i32_16x16x64_i8 v[122:125], v[118:121], v[194:197], v[122:125]
	v_mfma_i32_16x16x64_i8 v[94:97], v[106:109], v[202:205], v[94:97]
	v_mfma_i32_16x16x64_i8 v[90:93], v[118:121], v[202:205], v[90:93]
	v_mfma_i32_16x16x64_i8 v[82:85], v[106:109], v[210:213], v[82:85]
	v_mfma_i32_16x16x64_i8 v[74:77], v[118:121], v[210:213], v[74:77]
	v_mfma_i32_16x16x64_i8 v[134:137], v[156:159], v[182:185], v[134:137]
	v_mfma_i32_16x16x64_i8 v[130:133], v[174:177], v[182:185], v[130:133]
	v_mfma_i32_16x16x64_i8 v[110:113], v[156:159], v[190:193], v[110:113]
	v_mfma_i32_16x16x64_i8 v[98:101], v[174:177], v[190:193], v[98:101]
	v_mfma_i32_16x16x64_i8 v[86:89], v[156:159], v[198:201], v[86:89]
	v_mfma_i32_16x16x64_i8 v[78:81], v[174:177], v[198:201], v[78:81]
	v_mfma_i32_16x16x64_i8 v[70:73], v[156:159], v[206:209], v[70:73]
	v_mfma_i32_16x16x64_i8 v[66:69], v[174:177], v[206:209], v[66:69]
	v_mfma_i32_16x16x64_i8 v[134:137], v[170:173], v[186:189], v[134:137]
	v_mfma_i32_16x16x64_i8 v[130:133], v[178:181], v[186:189], v[130:133]
	v_mfma_i32_16x16x64_i8 v[110:113], v[170:173], v[194:197], v[110:113]
	v_mfma_i32_16x16x64_i8 v[98:101], v[178:181], v[194:197], v[98:101]
	v_mfma_i32_16x16x64_i8 v[86:89], v[170:173], v[202:205], v[86:89]
	v_mfma_i32_16x16x64_i8 v[78:81], v[178:181], v[202:205], v[78:81]
	v_mfma_i32_16x16x64_i8 v[70:73], v[170:173], v[210:213], v[70:73]
	v_mfma_i32_16x16x64_i8 v[66:69], v[178:181], v[210:213], v[66:69]
	s_barrier
	s_add_i32 s36, s62, s41
	v_lshl_add_u64 v[160:161], v[160:161], 0, s[16:17]
	s_mov_b32 m0, s36
	ds_read_b128 v[182:185], v168 offset:49152
	ds_read_b128 v[186:189], v168 offset:50176
	ds_read_b128 v[190:193], v168 offset:51200
	ds_read_b128 v[194:197], v168 offset:52224
	ds_read_b128 v[198:201], v168 offset:53248
	ds_read_b128 v[202:205], v168 offset:54272
	ds_read_b128 v[206:209], v168 offset:55296
	ds_read_b128 v[210:213], v168 offset:56320
	global_load_lds_dwordx4 v[160:161], off
	s_add_i32 m0, s36, 0x2000
	s_add_u32 s34, s34, 0x80080
	v_lshl_add_u64 v[160:161], v[214:215], 0, s[16:17]
	s_addc_u32 s35, s35, 0
	s_add_i32 s36, s63, s41
	global_load_lds_dwordx4 v[160:161], off
	v_lshl_add_u64 v[160:161], s[34:35], 0, v[146:147]
	s_mov_b32 m0, s36
	s_nop 0
	global_load_lds_dwordx4 v[160:161], off
	v_lshl_add_u64 v[160:161], s[34:35], 0, v[148:149]
	s_add_i32 m0, s36, 0x2000
	s_nop 0
	global_load_lds_dwordx4 v[160:161], off
	v_lshl_add_u64 v[160:161], v[216:217], 0, s[16:17]
	s_mov_b32 m0, s47
	s_nop 0
	global_load_lds_dwordx4 v[160:161], off
	v_lshl_add_u64 v[160:161], v[218:219], 0, s[16:17]
	s_mov_b32 m0, s48
	s_nop 0
	global_load_lds_dwordx4 v[160:161], off
	s_waitcnt vmcnt(8)
	s_waitcnt lgkmcnt(0)
	s_barrier
	s_waitcnt lgkmcnt(0)
	v_mfma_i32_16x16x64_i8 v[62:65], v[102:105], v[182:185], v[62:65]
	v_mfma_i32_16x16x64_i8 v[58:61], v[114:117], v[182:185], v[58:61]
	v_mfma_i32_16x16x64_i8 v[50:53], v[102:105], v[190:193], v[50:53]
	v_mfma_i32_16x16x64_i8 v[42:45], v[114:117], v[190:193], v[42:45]
	v_mfma_i32_16x16x64_i8 v[30:33], v[102:105], v[198:201], v[30:33]
	v_mfma_i32_16x16x64_i8 v[26:29], v[114:117], v[198:201], v[26:29]
	v_mfma_i32_16x16x64_i8 v[18:21], v[102:105], v[206:209], v[18:21]
	v_mfma_i32_16x16x64_i8 v[10:13], v[114:117], v[206:209], v[10:13]
	v_mfma_i32_16x16x64_i8 v[62:65], v[106:109], v[186:189], v[62:65]
	v_mfma_i32_16x16x64_i8 v[58:61], v[118:121], v[186:189], v[58:61]
	v_mfma_i32_16x16x64_i8 v[50:53], v[106:109], v[194:197], v[50:53]
	v_mfma_i32_16x16x64_i8 v[42:45], v[118:121], v[194:197], v[42:45]
	v_mfma_i32_16x16x64_i8 v[30:33], v[106:109], v[202:205], v[30:33]
	v_mfma_i32_16x16x64_i8 v[26:29], v[118:121], v[202:205], v[26:29]
	v_mfma_i32_16x16x64_i8 v[18:21], v[106:109], v[210:213], v[18:21]
	v_mfma_i32_16x16x64_i8 v[10:13], v[118:121], v[210:213], v[10:13]
	v_mfma_i32_16x16x64_i8 v[54:57], v[156:159], v[182:185], v[54:57]
	v_mfma_i32_16x16x64_i8 v[46:49], v[174:177], v[182:185], v[46:49]
	v_mfma_i32_16x16x64_i8 v[38:41], v[156:159], v[190:193], v[38:41]
	v_mfma_i32_16x16x64_i8 v[34:37], v[174:177], v[190:193], v[34:37]
	v_mfma_i32_16x16x64_i8 v[22:25], v[156:159], v[198:201], v[22:25]
	v_mfma_i32_16x16x64_i8 v[14:17], v[174:177], v[198:201], v[14:17]
	v_mfma_i32_16x16x64_i8 v[6:9], v[156:159], v[206:209], v[6:9]
	v_mfma_i32_16x16x64_i8 v[2:5], v[174:177], v[206:209], v[2:5]
	v_mfma_i32_16x16x64_i8 v[54:57], v[170:173], v[186:189], v[54:57]
	v_mfma_i32_16x16x64_i8 v[46:49], v[178:181], v[186:189], v[46:49]
	v_mfma_i32_16x16x64_i8 v[38:41], v[170:173], v[194:197], v[38:41]
	v_mfma_i32_16x16x64_i8 v[34:37], v[178:181], v[194:197], v[34:37]
	v_mfma_i32_16x16x64_i8 v[22:25], v[170:173], v[202:205], v[22:25]
	v_mfma_i32_16x16x64_i8 v[14:17], v[178:181], v[202:205], v[14:17]
	v_mfma_i32_16x16x64_i8 v[6:9], v[170:173], v[210:213], v[6:9]
	v_mfma_i32_16x16x64_i8 v[2:5], v[178:181], v[210:213], v[2:5]
	s_barrier
	s_add_i32 s61, s61, 2
	s_add_u32 s30, s30, 0x100
	s_addc_u32 s31, s31, 0
	s_add_u32 s59, s59, 0x100
	s_addc_u32 s60, s60, 0
	s_cmp_gt_u32 s61, 29
	s_branch .LBB0_2231

;     static __device__ __forceinline__ size_t a_off(const Gemm& g, const Unit& u) { return (size_t)u.pm * 256 * g.lda * 2; }
;     static __device__ __forceinline__ size_t b_off(const Gemm& g, const Unit& u) { return (size_t)u.pn * 256 * g.ldb * 2; }
;     static __device__ __forceinline__ size_t a_off(const Gemm& g, const Unit& u) { return ((size_t)u.pm * 256 * g.lda + (size_t)(u.pn >> 1) * 256) * 2; }
;     static __device__ __forceinline__ size_t b_off(const Gemm& g, const Unit& u) { return (size_t)u.pn * 256 * g.ldb * 2; }
;     __host__ __device__ bool next(int i, Unit& u) const { const long L = (long)i * G + c; if (L >= limit) return false; tile_of((int)L, u); return true; }
;     __host__ __device__ bool next(int i, Unit& u) const { if (i > 0 || c >= nrem * 8) return false; base.tile_of(first + c % nrem, u); u.tl = c % nrem; u.ks = c / nrem; return true; }
;     static __device__ __forceinline__ size_t a_off(const Gemm& g, const Unit& u) { return ((size_t)u.pm * 256 * g.lda + (size_t)u.ks * g.K) * 2; }
;     static __device__ __forceinline__ size_t b_off(const Gemm& g, const Unit& u) { return ((size_t)u.pn * 256 * g.ldb + (size_t)u.ks * g.K) * 2; }
; template <class Epi, class Geom, class Sched, bool ALIGN_EPI, bool I8 = false>
; __device__ __forceinline__ void gemm_phase(LAS unsigned char* lds, const Gemm g, const Sched& S, const Epi& E) {
;     ...
;     for (;;) {
;         const bool has_next = S.next(ui + 1, nxt);
;         const char* nA = has_next ? (const char*)g.A + Geom::a_off(g, nxt) : cA; const char* nB = has_next ? (const char*)g.Bt + Geom::b_off(g, nxt) : cB;
; #pragma unroll 1
;         for (int t = 0; t < nt; t += 2) {
;             const bool last = (t == nt - 2);
;             const char* a1 = cA + (size_t)(t + 1) * kstep;
;             const char* a2 = last ? nA : cA + (size_t)(t + 2) * kstep; const char* b2 = last ? nB : cB + (size_t)(t + 2) * kstep;
;             const char* a3 = a2 + kstep; const char* b3 = b2 + kstep;
.LBB0_2519:
	s_ashr_i32 s57, s56, 31
	s_lshl_b64 s[58:59], s[56:57], 20
	s_add_u32 s58, s1, s58
	s_addc_u32 s59, s74, s59
	s_and_b64 s[60:61], s[18:19], exec
	s_cselect_b32 s3, s59, s21
	s_cselect_b32 s33, s58, s20
	s_ashr_i32 s85, s84, 31
	s_lshl_b64 s[60:61], s[84:85], 20
	s_add_u32 s60, s75, s60
	s_addc_u32 s61, s76, s61
	s_and_b64 s[66:67], s[18:19], exec
	s_cselect_b32 s55, s61, s63
	s_cselect_b32 s57, s60, s62
	s_add_u32 s20, s20, 0x80080
	s_addc_u32 s21, s21, 0
	s_add_u32 s65, s62, 0x100
	s_addc_u32 s68, s63, 0
	s_mov_b32 s69, -2
	s_branch .Lpz0_0

; #define PG8_STAGE(bufoff, gbase, voff) do { _Pragma("unroll") for (int _i = 0; _i < 2; ++_i) \
;         __builtin_amdgcn_global_load_lds((const unsigned*)((const char*)(gbase) + (voff)[_i]), (LAS unsigned*)(lds + (bufoff) + ldsw + _i * 8192), 16, 0, 0); } while (0)
; #define PG8_LDA(dst, b, h) do { _Pragma("unroll") for (int m = 0; m < 4; ++m) _Pragma("unroll") for (int k = 0; k < 2; ++k) dst[m][k] = *(const LAS bf16x8*)(lds + PG8_SA(b, h) + aoff + m * 2048 + k * 1024); } while (0)
; #define PG8_LDB(dst, b, h) do { _Pragma("unroll") for (int n = 0; n < 2; ++n) _Pragma("unroll") for (int k = 0; k < 2; ++k) dst[n][k] = *(const LAS bf16x8*)(lds + PG8_SB(b, h) + boff + n * 2048 + k * 1024); } while (0)
; #define PG8_WAIT_V(n) asm volatile("s_waitcnt vmcnt(" #n ")" ::: "memory")
; #define PG8_WAIT_L(n) asm volatile("s_waitcnt lgkmcnt(" #n ")" ::: "memory")
; #define PG8_BAR __builtin_amdgcn_s_barrier()
; #define PG8_SCHED __builtin_amdgcn_sched_barrier(0)
; template <class Epi, class Geom, class Sched, bool ALIGN_EPI, bool I8 = false>
; __device__ __forceinline__ void gemm_phase(LAS unsigned char* lds, const Gemm g, const Sched& S, const Epi& E) {
;     ...
;             PG8_LDB(B0, 0, 0); PG8_LDB(B1, 0, 1); PG8_SCHED; PG8_LDA(At, 0, 0); PG8_STAGE(PG8_SA(1, 1), a1 + hsA, voffA);
;             PG8_WAIT_V(8); PG8_WAIT_L(0); PG8_BAR; PG8_MMA(0, 0, At, B0); PG8_MMA(0, 1, At, B1); PG8_BAR; PG8_SCHED;
;             PG8_LDA(At, 0, 1); PG8_STAGE(PG8_SB(0, 0), b2, voffB); PG8_STAGE(PG8_SB(0, 1), b2 + hsB, voffB); PG8_STAGE(PG8_SA(0, 0), a2, voffA);
;             PG8_WAIT_V(8); PG8_WAIT_L(0); PG8_BAR; PG8_MMA(1, 0, At, B0); PG8_MMA(1, 1, At, B1); PG8_BAR; PG8_SCHED;
.Lpz0_0:
	ds_read_b128 v[130:133], v248
	ds_read_b128 v[134:137], v248 offset:1024
	ds_read_b128 v[138:141], v248 offset:2048
	ds_read_b128 v[142:145], v248 offset:3072
	ds_read_b128 v[146:149], v249
	ds_read_b128 v[150:153], v249 offset:1024
	ds_read_b128 v[154:157], v249 offset:2048
	ds_read_b128 v[158:161], v249 offset:3072
	s_add_u32 s62, s20, 0xfff80080
	s_addc_u32 s63, s21, -1
	s_cmp_eq_u32 s69, 28
	s_cselect_b32 s67, s3, s63
	s_cselect_b32 s66, s33, s62
	s_cselect_b32 s63, s55, s68
	s_cselect_b32 s62, s57, s65
	v_lshl_add_u64 v[166:167], s[20:21], 0, v[182:183]
	s_add_i32 m0, s78, 0xc000
	ds_read_b128 v[162:165], v250
	ds_read_b128 v[190:193], v250 offset:1024
	ds_read_b128 v[194:197], v250 offset:2048
	ds_read_b128 v[198:201], v250 offset:3072
	ds_read_b128 v[202:205], v250 offset:4096
	ds_read_b128 v[206:209], v250 offset:5120
	ds_read_b128 v[210:213], v250 offset:6144
	ds_read_b128 v[214:217], v250 offset:7168
	global_load_lds_dwordx4 v[166:167], off
	v_lshl_add_u64 v[166:167], s[20:21], 0, v[184:185]
	s_add_i32 m0, s78, 0xe000
	s_nop 0
	global_load_lds_dwordx4 v[166:167], off
	s_waitcnt vmcnt(8)
	s_waitcnt lgkmcnt(0)
	s_barrier
	s_waitcnt lgkmcnt(0)
	v_mfma_i32_16x16x64_i8 v[126:129], v[130:133], v[162:165], 0
	v_mfma_i32_16x16x64_i8 v[122:125], v[138:141], v[162:165], 0
	v_mfma_i32_16x16x64_i8 v[114:117], v[130:133], v[194:197], 0
	v_mfma_i32_16x16x64_i8 v[106:109], v[138:141], v[194:197], 0
	v_mfma_i32_16x16x64_i8 v[102:105], v[130:133], v[202:205], 0
	v_mfma_i32_16x16x64_i8 v[94:97], v[138:141], v[202:205], 0
	v_mfma_i32_16x16x64_i8 v[86:89], v[130:133], v[210:213], 0
	v_mfma_i32_16x16x64_i8 v[78:81], v[138:141], v[210:213], 0
	v_mfma_i32_16x16x64_i8 v[126:129], v[134:137], v[190:193], v[126:129]
	v_mfma_i32_16x16x64_i8 v[122:125], v[142:145], v[190:193], v[122:125]
	v_mfma_i32_16x16x64_i8 v[114:117], v[134:137], v[198:201], v[114:117]
	v_mfma_i32_16x16x64_i8 v[106:109], v[142:145], v[198:201], v[106:109]
	v_mfma_i32_16x16x64_i8 v[102:105], v[134:137], v[206:209], v[102:105]
	v_mfma_i32_16x16x64_i8 v[94:97], v[142:145], v[206:209], v[94:97]
	v_mfma_i32_16x16x64_i8 v[86:89], v[134:137], v[214:217], v[86:89]
	v_mfma_i32_16x16x64_i8 v[78:81], v[142:145], v[214:217], v[78:81]
	v_mfma_i32_16x16x64_i8 v[118:121], v[146:149], v[162:165], 0
	v_mfma_i32_16x16x64_i8 v[82:85], v[154:157], v[162:165], 0
	v_mfma_i32_16x16x64_i8 v[110:113], v[146:149], v[194:197], 0
	v_mfma_i32_16x16x64_i8 v[74:77], v[154:157], v[194:197], 0
	v_mfma_i32_16x16x64_i8 v[98:101], v[146:149], v[202:205], 0
	v_mfma_i32_16x16x64_i8 v[66:69], v[154:157], v[202:205], 0
	v_mfma_i32_16x16x64_i8 v[90:93], v[146:149], v[210:213], 0
	v_mfma_i32_16x16x64_i8 v[58:61], v[154:157], v[210:213], 0
	v_mfma_i32_16x16x64_i8 v[118:121], v[150:153], v[190:193], v[118:121]
	v_mfma_i32_16x16x64_i8 v[82:85], v[158:161], v[190:193], v[82:85]
	v_mfma_i32_16x16x64_i8 v[110:113], v[150:153], v[198:201], v[110:113]
	v_mfma_i32_16x16x64_i8 v[74:77], v[158:161], v[198:201], v[74:77]
	v_mfma_i32_16x16x64_i8 v[98:101], v[150:153], v[206:209], v[98:101]
	v_mfma_i32_16x16x64_i8 v[66:69], v[158:161], v[206:209], v[66:69]
	v_mfma_i32_16x16x64_i8 v[90:93], v[150:153], v[214:217], v[90:93]
	v_mfma_i32_16x16x64_i8 v[58:61], v[158:161], v[214:217], v[58:61]
	s_barrier
	s_add_i32 s70, s92, s77
	v_lshl_add_u64 v[166:167], s[62:63], 0, v[170:171]
	s_mov_b32 m0, s70
	ds_read_b128 v[162:165], v250 offset:16384
	ds_read_b128 v[190:193], v250 offset:17408
	ds_read_b128 v[194:197], v250 offset:18432
	ds_read_b128 v[198:201], v250 offset:19456
	ds_read_b128 v[202:205], v250 offset:20480
	ds_read_b128 v[206:209], v250 offset:21504
	ds_read_b128 v[210:213], v250 offset:22528
	ds_read_b128 v[214:217], v250 offset:23552
	global_load_lds_dwordx4 v[166:167], off
	s_add_i32 m0, s70, 0x2000
	s_add_u32 s70, s62, 0x80000
	v_lshl_add_u64 v[218:219], s[62:63], 0, v[174:175]
	s_addc_u32 s71, s63, 0
	s_add_i32 s72, s93, s77
	global_load_lds_dwordx4 v[218:219], off
	v_lshl_add_u64 v[220:221], s[70:71], 0, v[170:171]
	s_mov_b32 m0, s72
	v_lshl_add_u64 v[222:223], s[66:67], 0, v[172:173]
	global_load_lds_dwordx4 v[220:221], off
	v_lshl_add_u64 v[220:221], s[70:71], 0, v[174:175]
	s_add_i32 m0, s72, 0x2000
	s_nop 0
	global_load_lds_dwordx4 v[220:221], off
	v_lshl_add_u64 v[220:221], s[66:67], 0, v[168:169]
	s_mov_b32 m0, s78
	s_nop 0
	global_load_lds_dwordx4 v[220:221], off
	s_mov_b32 m0, s79
	s_nop 0
	global_load_lds_dwordx4 v[222:223], off
	s_waitcnt vmcnt(8)
	s_waitcnt lgkmcnt(0)
	s_barrier
	s_waitcnt lgkmcnt(0)
	v_mfma_i32_16x16x64_i8 v[70:73], v[130:133], v[162:165], 0
	v_mfma_i32_16x16x64_i8 v[62:65], v[138:141], v[162:165], 0
	v_mfma_i32_16x16x64_i8 v[38:41], v[130:133], v[194:197], 0
	v_mfma_i32_16x16x64_i8 v[54:57], v[138:141], v[194:197], 0
	v_mfma_i32_16x16x64_i8 v[30:33], v[130:133], v[202:205], 0
	v_mfma_i32_16x16x64_i8 v[50:53], v[138:141], v[202:205], 0
	v_mfma_i32_16x16x64_i8 v[26:29], v[130:133], v[210:213], 0
	v_mfma_i32_16x16x64_i8 v[18:21], v[138:141], v[210:213], 0
	v_mfma_i32_16x16x64_i8 v[70:73], v[134:137], v[190:193], v[70:73]
	v_mfma_i32_16x16x64_i8 v[62:65], v[142:145], v[190:193], v[62:65]
	v_mfma_i32_16x16x64_i8 v[38:41], v[134:137], v[198:201], v[38:41]
	v_mfma_i32_16x16x64_i8 v[54:57], v[142:145], v[198:201], v[54:57]
	v_mfma_i32_16x16x64_i8 v[30:33], v[134:137], v[206:209], v[30:33]
	v_mfma_i32_16x16x64_i8 v[50:53], v[142:145], v[206:209], v[50:53]
	v_mfma_i32_16x16x64_i8 v[26:29], v[134:137], v[214:217], v[26:29]
	v_mfma_i32_16x16x64_i8 v[18:21], v[142:145], v[214:217], v[18:21]
	v_mfma_i32_16x16x64_i8 v[46:49], v[146:149], v[162:165], 0
	v_mfma_i32_16x16x64_i8 v[14:17], v[154:157], v[162:165], 0
	v_mfma_i32_16x16x64_i8 v[42:45], v[146:149], v[194:197], 0
	v_mfma_i32_16x16x64_i8 v[10:13], v[154:157], v[194:197], 0
	v_mfma_i32_16x16x64_i8 v[34:37], v[146:149], v[202:205], 0
	v_mfma_i32_16x16x64_i8 v[6:9], v[154:157], v[202:205], 0
	v_mfma_i32_16x16x64_i8 v[22:25], v[146:149], v[210:213], 0
	v_mfma_i32_16x16x64_i8 v[2:5], v[154:157], v[210:213], 0
	v_mfma_i32_16x16x64_i8 v[46:49], v[150:153], v[190:193], v[46:49]
	v_mfma_i32_16x16x64_i8 v[14:17], v[158:161], v[190:193], v[14:17]
	v_mfma_i32_16x16x64_i8 v[42:45], v[150:153], v[198:201], v[42:45]
	v_mfma_i32_16x16x64_i8 v[10:13], v[158:161], v[198:201], v[10:13]
	v_mfma_i32_16x16x64_i8 v[34:37], v[150:153], v[206:209], v[34:37]
	v_mfma_i32_16x16x64_i8 v[6:9], v[158:161], v[206:209], v[6:9]
	v_mfma_i32_16x16x64_i8 v[22:25], v[150:153], v[214:217], v[22:25]
	v_mfma_i32_16x16x64_i8 v[2:5], v[158:161], v[214:217], v[2:5]
	s_barrier
; #define PG8_STAGE(bufoff, gbase, voff) do { _Pragma("unroll") for (int _i = 0; _i < 2; ++_i) \
;         __builtin_amdgcn_global_load_lds((const unsigned*)((const char*)(gbase) + (voff)[_i]), (LAS unsigned*)(lds + (bufoff) + ldsw + _i * 8192), 16, 0, 0); } while (0)
; #define PG8_LDA(dst, b, h) do { _Pragma("unroll") for (int m = 0; m < 4; ++m) _Pragma("unroll") for (int k = 0; k < 2; ++k) dst[m][k] = *(const LAS bf16x8*)(lds + PG8_SA(b, h) + aoff + m * 2048 + k * 1024); } while (0)
; #define PG8_LDB(dst, b, h) do { _Pragma("unroll") for (int n = 0; n < 2; ++n) _Pragma("unroll") for (int k = 0; k < 2; ++k) dst[n][k] = *(const LAS bf16x8*)(lds + PG8_SB(b, h) + boff + n * 2048 + k * 1024); } while (0)
; #define PG8_WAIT_V(n) asm volatile("s_waitcnt vmcnt(" #n ")" ::: "memory")
; #define PG8_WAIT_L(n) asm volatile("s_waitcnt lgkmcnt(" #n ")" ::: "memory")
; #define PG8_BAR __builtin_amdgcn_s_barrier()
; #define PG8_SCHED __builtin_amdgcn_sched_barrier(0)
; template <class Epi, class Geom, class Sched, bool ALIGN_EPI, bool I8 = false>
; __device__ __forceinline__ void gemm_phase(LAS unsigned char* lds, const Gemm g, const Sched& S, const Epi& E) {
;     ...
;             PG8_LDB(B0, 1, 0); PG8_LDB(B1, 1, 1); PG8_SCHED; PG8_LDA(At, 1, 0); PG8_STAGE(PG8_SA(0, 1), a2 + hsA, voffA);
;             PG8_WAIT_V(8); PG8_WAIT_L(0); PG8_BAR; PG8_MMA(0, 0, At, B0); PG8_MMA(0, 1, At, B1); PG8_BAR; PG8_SCHED;
;             PG8_LDA(At, 1, 1); PG8_STAGE(PG8_SB(1, 0), b3, voffB); PG8_STAGE(PG8_SB(1, 1), b3 + hsB, voffB); PG8_STAGE(PG8_SA(1, 0), a3, voffA);
;             PG8_WAIT_V(8); PG8_WAIT_L(0); PG8_BAR; PG8_MMA(1, 0, At, B0); PG8_MMA(1, 1, At, B1); PG8_BAR; PG8_SCHED;
;         }
	s_add_i32 s70, 0, 0x18000
	s_add_i32 s71, 0, 0x1c000
	v_add_u32_e32 v142, s70, v1
	v_add_u32_e32 v158, s71, v1
	ds_read_b128 v[130:133], v142
	ds_read_b128 v[134:137], v142 offset:1024
	ds_read_b128 v[138:141], v142 offset:2048
	ds_read_b128 v[142:145], v142 offset:3072
	ds_read_b128 v[146:149], v158
	ds_read_b128 v[150:153], v158 offset:1024
	ds_read_b128 v[154:157], v158 offset:2048
	ds_read_b128 v[158:161], v158 offset:3072
	s_add_u32 s66, s66, 0x80000
	s_addc_u32 s67, s67, 0
	s_mov_b32 m0, s80
	v_lshl_add_u64 v[224:225], s[66:67], 0, v[168:169]
	ds_read_b128 v[162:165], v250 offset:32768
	ds_read_b128 v[190:193], v250 offset:33792
	ds_read_b128 v[194:197], v250 offset:34816
	ds_read_b128 v[198:201], v250 offset:35840
	ds_read_b128 v[202:205], v250 offset:36864
	ds_read_b128 v[206:209], v250 offset:37888
	ds_read_b128 v[210:213], v250 offset:38912
	ds_read_b128 v[214:217], v250 offset:39936
	global_load_lds_dwordx4 v[224:225], off
	v_lshl_add_u64 v[224:225], s[66:67], 0, v[172:173]
	s_mov_b32 m0, s81
	s_nop 0
	global_load_lds_dwordx4 v[224:225], off
	s_waitcnt vmcnt(8)
	s_waitcnt lgkmcnt(0)
	s_barrier
	s_waitcnt lgkmcnt(0)
	v_mfma_i32_16x16x64_i8 v[126:129], v[130:133], v[162:165], v[126:129]
	v_mfma_i32_16x16x64_i8 v[122:125], v[138:141], v[162:165], v[122:125]
	v_mfma_i32_16x16x64_i8 v[114:117], v[130:133], v[194:197], v[114:117]
	v_mfma_i32_16x16x64_i8 v[106:109], v[138:141], v[194:197], v[106:109]
	v_mfma_i32_16x16x64_i8 v[102:105], v[130:133], v[202:205], v[102:105]
	v_mfma_i32_16x16x64_i8 v[94:97], v[138:141], v[202:205], v[94:97]
	v_mfma_i32_16x16x64_i8 v[86:89], v[130:133], v[210:213], v[86:89]
	v_mfma_i32_16x16x64_i8 v[78:81], v[138:141], v[210:213], v[78:81]
	v_mfma_i32_16x16x64_i8 v[126:129], v[134:137], v[190:193], v[126:129]
	v_mfma_i32_16x16x64_i8 v[122:125], v[142:145], v[190:193], v[122:125]
	v_mfma_i32_16x16x64_i8 v[114:117], v[134:137], v[198:201], v[114:117]
	v_mfma_i32_16x16x64_i8 v[106:109], v[142:145], v[198:201], v[106:109]
	v_mfma_i32_16x16x64_i8 v[102:105], v[134:137], v[206:209], v[102:105]
	v_mfma_i32_16x16x64_i8 v[94:97], v[142:145], v[206:209], v[94:97]
	v_mfma_i32_16x16x64_i8 v[86:89], v[134:137], v[214:217], v[86:89]
	v_mfma_i32_16x16x64_i8 v[78:81], v[142:145], v[214:217], v[78:81]
	v_mfma_i32_16x16x64_i8 v[118:121], v[146:149], v[162:165], v[118:121]
	v_mfma_i32_16x16x64_i8 v[82:85], v[154:157], v[162:165], v[82:85]
	v_mfma_i32_16x16x64_i8 v[110:113], v[146:149], v[194:197], v[110:113]
	v_mfma_i32_16x16x64_i8 v[74:77], v[154:157], v[194:197], v[74:77]
	v_mfma_i32_16x16x64_i8 v[98:101], v[146:149], v[202:205], v[98:101]
	v_mfma_i32_16x16x64_i8 v[66:69], v[154:157], v[202:205], v[66:69]
	v_mfma_i32_16x16x64_i8 v[90:93], v[146:149], v[210:213], v[90:93]
	v_mfma_i32_16x16x64_i8 v[58:61], v[154:157], v[210:213], v[58:61]
	v_mfma_i32_16x16x64_i8 v[118:121], v[150:153], v[190:193], v[118:121]
	v_mfma_i32_16x16x64_i8 v[82:85], v[158:161], v[190:193], v[82:85]
	v_mfma_i32_16x16x64_i8 v[110:113], v[150:153], v[198:201], v[110:113]
	v_mfma_i32_16x16x64_i8 v[74:77], v[158:161], v[198:201], v[74:77]
	v_mfma_i32_16x16x64_i8 v[98:101], v[150:153], v[206:209], v[98:101]
	v_mfma_i32_16x16x64_i8 v[66:69], v[158:161], v[206:209], v[66:69]
	v_mfma_i32_16x16x64_i8 v[90:93], v[150:153], v[214:217], v[90:93]
	v_mfma_i32_16x16x64_i8 v[58:61], v[158:161], v[214:217], v[58:61]
	s_barrier
	s_add_i32 s66, s70, s77
	v_lshl_add_u64 v[166:167], v[166:167], 0, s[28:29]
	s_mov_b32 m0, s66
	ds_read_b128 v[162:165], v250 offset:49152
	ds_read_b128 v[190:193], v250 offset:50176
	ds_read_b128 v[194:197], v250 offset:51200
	ds_read_b128 v[198:201], v250 offset:52224
	ds_read_b128 v[202:205], v250 offset:53248
	ds_read_b128 v[206:209], v250 offset:54272
	ds_read_b128 v[210:213], v250 offset:55296
	ds_read_b128 v[214:217], v250 offset:56320
	global_load_lds_dwordx4 v[166:167], off
	s_add_i32 m0, s66, 0x2000
	s_add_u32 s62, s62, 0x80080
	v_lshl_add_u64 v[166:167], v[218:219], 0, s[28:29]
	s_addc_u32 s63, s63, 0
	s_add_i32 s66, s71, s77
	global_load_lds_dwordx4 v[166:167], off
	v_lshl_add_u64 v[166:167], s[62:63], 0, v[170:171]
	s_mov_b32 m0, s66
	s_nop 0
	global_load_lds_dwordx4 v[166:167], off
	v_lshl_add_u64 v[166:167], s[62:63], 0, v[174:175]
	s_add_i32 m0, s66, 0x2000
	s_nop 0
	global_load_lds_dwordx4 v[166:167], off
	v_lshl_add_u64 v[166:167], v[220:221], 0, s[28:29]
	s_mov_b32 m0, s88
	s_nop 0
	global_load_lds_dwordx4 v[166:167], off
	v_lshl_add_u64 v[166:167], v[222:223], 0, s[28:29]
	s_mov_b32 m0, s89
	s_nop 0
	global_load_lds_dwordx4 v[166:167], off
	s_waitcnt vmcnt(8)
	s_waitcnt lgkmcnt(0)
	s_barrier
	s_waitcnt lgkmcnt(0)
	v_mfma_i32_16x16x64_i8 v[70:73], v[130:133], v[162:165], v[70:73]
	v_mfma_i32_16x16x64_i8 v[62:65], v[138:141], v[162:165], v[62:65]
	v_mfma_i32_16x16x64_i8 v[38:41], v[130:133], v[194:197], v[38:41]
	v_mfma_i32_16x16x64_i8 v[54:57], v[138:141], v[194:197], v[54:57]
	v_mfma_i32_16x16x64_i8 v[30:33], v[130:133], v[202:205], v[30:33]
	v_mfma_i32_16x16x64_i8 v[50:53], v[138:141], v[202:205], v[50:53]
	v_mfma_i32_16x16x64_i8 v[26:29], v[130:133], v[210:213], v[26:29]
	v_mfma_i32_16x16x64_i8 v[18:21], v[138:141], v[210:213], v[18:21]
	v_mfma_i32_16x16x64_i8 v[70:73], v[134:137], v[190:193], v[70:73]
	v_mfma_i32_16x16x64_i8 v[62:65], v[142:145], v[190:193], v[62:65]
	v_mfma_i32_16x16x64_i8 v[38:41], v[134:137], v[198:201], v[38:41]
	v_mfma_i32_16x16x64_i8 v[54:57], v[142:145], v[198:201], v[54:57]
	v_mfma_i32_16x16x64_i8 v[30:33], v[134:137], v[206:209], v[30:33]
	v_mfma_i32_16x16x64_i8 v[50:53], v[142:145], v[206:209], v[50:53]
	v_mfma_i32_16x16x64_i8 v[26:29], v[134:137], v[214:217], v[26:29]
	v_mfma_i32_16x16x64_i8 v[18:21], v[142:145], v[214:217], v[18:21]
	v_mfma_i32_16x16x64_i8 v[46:49], v[146:149], v[162:165], v[46:49]
	v_mfma_i32_16x16x64_i8 v[14:17], v[154:157], v[162:165], v[14:17]
	v_mfma_i32_16x16x64_i8 v[42:45], v[146:149], v[194:197], v[42:45]
	v_mfma_i32_16x16x64_i8 v[10:13], v[154:157], v[194:197], v[10:13]
	v_mfma_i32_16x16x64_i8 v[34:37], v[146:149], v[202:205], v[34:37]
	v_mfma_i32_16x16x64_i8 v[6:9], v[154:157], v[202:205], v[6:9]
	v_mfma_i32_16x16x64_i8 v[22:25], v[146:149], v[210:213], v[22:25]
	v_mfma_i32_16x16x64_i8 v[2:5], v[154:157], v[210:213], v[2:5]
	v_mfma_i32_16x16x64_i8 v[46:49], v[150:153], v[190:193], v[46:49]
	v_mfma_i32_16x16x64_i8 v[14:17], v[158:161], v[190:193], v[14:17]
	v_mfma_i32_16x16x64_i8 v[42:45], v[150:153], v[198:201], v[42:45]
	v_mfma_i32_16x16x64_i8 v[10:13], v[158:161], v[198:201], v[10:13]
	v_mfma_i32_16x16x64_i8 v[34:37], v[150:153], v[206:209], v[34:37]
	v_mfma_i32_16x16x64_i8 v[6:9], v[158:161], v[206:209], v[6:9]
	v_mfma_i32_16x16x64_i8 v[22:25], v[150:153], v[214:217], v[22:25]
	v_mfma_i32_16x16x64_i8 v[2:5], v[158:161], v[214:217], v[2:5]
	s_barrier
	s_add_i32 s69, s69, 2
	s_add_u32 s20, s20, 0x100
	s_addc_u32 s21, s21, 0
	s_add_u32 s65, s65, 0x100
	s_addc_u32 s68, s68, 0
	s_cmp_gt_u32 s69, 29
	s_branch .LBB0_2520

;     static __device__ __forceinline__ size_t a_off(const Gemm& g, const Unit& u) { return (size_t)u.pm * 256 * g.lda * 2; }
;     static __device__ __forceinline__ size_t b_off(const Gemm& g, const Unit& u) { return (size_t)u.pn * 256 * g.ldb * 2; }
;     static __device__ __forceinline__ size_t a_off(const Gemm& g, const Unit& u) { return ((size_t)u.pm * 256 * g.lda + (size_t)(u.pn >> 1) * 256) * 2; }
;     static __device__ __forceinline__ size_t b_off(const Gemm& g, const Unit& u) { return (size_t)u.pn * 256 * g.ldb * 2; }
;     __host__ __device__ bool next(int i, Unit& u) const { const long L = (long)i * G + c; if (L >= limit) return false; tile_of((int)L, u); return true; }
;     __host__ __device__ bool next(int i, Unit& u) const { if (i > 0 || c >= nrem * 8) return false; base.tile_of(first + c % nrem, u); u.tl = c % nrem; u.ks = c / nrem; return true; }
;     static __device__ __forceinline__ size_t a_off(const Gemm& g, const Unit& u) { return ((size_t)u.pm * 256 * g.lda + (size_t)u.ks * g.K) * 2; }
;     static __device__ __forceinline__ size_t b_off(const Gemm& g, const Unit& u) { return ((size_t)u.pn * 256 * g.ldb + (size_t)u.ks * g.K) * 2; }
; template <class Epi, class Geom, class Sched, bool ALIGN_EPI, bool I8 = false>
; __device__ __forceinline__ void gemm_phase(LAS unsigned char* lds, const Gemm g, const Sched& S, const Epi& E) {
;     ...
;     for (;;) {
;         const bool has_next = S.next(ui + 1, nxt);
;         const char* nA = has_next ? (const char*)g.A + Geom::a_off(g, nxt) : cA; const char* nB = has_next ? (const char*)g.Bt + Geom::b_off(g, nxt) : cB;
; #pragma unroll 1
;         for (int t = 0; t < nt; t += 2) {
;             const bool last = (t == nt - 2);
;             const char* a1 = cA + (size_t)(t + 1) * kstep;
;             const char* a2 = last ? nA : cA + (size_t)(t + 2) * kstep; const char* b2 = last ? nB : cB + (size_t)(t + 2) * kstep;
;             const char* a3 = a2 + kstep; const char* b3 = b2 + kstep;
.LBB0_2871:
	s_add_u32 s36, s36, 0x180080
	s_addc_u32 s37, s37, 0
	s_add_u32 s60, s38, 0x100
	s_addc_u32 s61, s39, 0
	s_mov_b32 s62, -2
	s_branch .Lpz2_0

; #define PG8_STAGE(bufoff, gbase, voff) do { _Pragma("unroll") for (int _i = 0; _i < 2; ++_i) \
;         __builtin_amdgcn_global_load_lds((const unsigned*)((const char*)(gbase) + (voff)[_i]), (LAS unsigned*)(lds + (bufoff) + ldsw + _i * 8192), 16, 0, 0); } while (0)
; #define PG8_LDA(dst, b, h) do { _Pragma("unroll") for (int m = 0; m < 4; ++m) _Pragma("unroll") for (int k = 0; k < 2; ++k) dst[m][k] = *(const LAS bf16x8*)(lds + PG8_SA(b, h) + aoff + m * 2048 + k * 1024); } while (0)
; #define PG8_LDB(dst, b, h) do { _Pragma("unroll") for (int n = 0; n < 2; ++n) _Pragma("unroll") for (int k = 0; k < 2; ++k) dst[n][k] = *(const LAS bf16x8*)(lds + PG8_SB(b, h) + boff + n * 2048 + k * 1024); } while (0)
; #define PG8_WAIT_V(n) asm volatile("s_waitcnt vmcnt(" #n ")" ::: "memory")
; #define PG8_WAIT_L(n) asm volatile("s_waitcnt lgkmcnt(" #n ")" ::: "memory")
; #define PG8_BAR __builtin_amdgcn_s_barrier()
; #define PG8_SCHED __builtin_amdgcn_sched_barrier(0)
; template <class Epi, class Geom, class Sched, bool ALIGN_EPI, bool I8 = false>
; __device__ __forceinline__ void gemm_phase(LAS unsigned char* lds, const Gemm g, const Sched& S, const Epi& E) {
;     ...
;             PG8_LDB(B0, 0, 0); PG8_LDB(B1, 0, 1); PG8_SCHED; PG8_LDA(At, 0, 0); PG8_STAGE(PG8_SA(1, 1), a1 + hsA, voffA);
;             PG8_WAIT_V(8); PG8_WAIT_L(0); PG8_BAR; PG8_MMA(0, 0, At, B0); PG8_MMA(0, 1, At, B1); PG8_BAR; PG8_SCHED;
;             PG8_LDA(At, 0, 1); PG8_STAGE(PG8_SB(0, 0), b2, voffB); PG8_STAGE(PG8_SB(0, 1), b2 + hsB, voffB); PG8_STAGE(PG8_SA(0, 0), a2, voffA);
;             PG8_WAIT_V(8); PG8_WAIT_L(0); PG8_BAR; PG8_MMA(1, 0, At, B0); PG8_MMA(1, 1, At, B1); PG8_BAR; PG8_SCHED;
.Lpz2_0:
	ds_read_b128 v[90:93], v181
	ds_read_b128 v[98:101], v181 offset:1024
	ds_read_b128 v[102:105], v181 offset:2048
	ds_read_b128 v[160:163], v181 offset:3072
	ds_read_b128 v[182:185], v206
	ds_read_b128 v[186:189], v206 offset:1024
	ds_read_b128 v[190:193], v206 offset:2048
	ds_read_b128 v[194:197], v206 offset:3072
	s_add_u32 s38, s36, 0xffe80080
	s_addc_u32 s39, s37, -1
	s_cmpk_eq_i32 s62, 0x5c
	s_cselect_b32 s41, s1, s39
	s_cselect_b32 s40, s0, s38
	s_cselect_b32 s39, s35, s61
	s_cselect_b32 s38, s34, s60
	v_lshl_add_u64 v[152:153], s[36:37], 0, v[146:147]
	s_add_i32 m0, s33, 0xc000
	ds_read_b128 v[198:201], v207
	ds_read_b128 v[202:205], v207 offset:1024
	ds_read_b128 v[208:211], v207 offset:2048
	ds_read_b128 v[212:215], v207 offset:3072
	ds_read_b128 v[216:219], v207 offset:4096
	ds_read_b128 v[220:223], v207 offset:5120
	ds_read_b128 v[224:227], v207 offset:6144
	ds_read_b128 v[228:231], v207 offset:7168
	global_load_lds_dwordx4 v[152:153], off
	v_lshl_add_u64 v[152:153], s[36:37], 0, v[148:149]
	s_add_i32 m0, s33, 0xe000
	s_nop 0
	global_load_lds_dwordx4 v[152:153], off
	s_waitcnt vmcnt(8)
	s_waitcnt lgkmcnt(0)
	s_barrier
	s_waitcnt lgkmcnt(0)
	v_mfma_i32_16x16x64_i8 v[94:97], v[90:93], v[198:201], 0
	v_mfma_i32_16x16x64_i8 v[138:141], v[102:105], v[198:201], 0
	v_mfma_i32_16x16x64_i8 v[130:133], v[90:93], v[208:211], 0
	v_mfma_i32_16x16x64_i8 v[122:125], v[102:105], v[208:211], 0
	v_mfma_i32_16x16x64_i8 v[110:113], v[90:93], v[216:219], 0
	v_mfma_i32_16x16x64_i8 v[106:109], v[102:105], v[216:219], 0
	v_mfma_i32_16x16x64_i8 v[82:85], v[90:93], v[224:227], 0
	v_mfma_i32_16x16x64_i8 v[74:77], v[102:105], v[224:227], 0
	v_mfma_i32_16x16x64_i8 v[94:97], v[98:101], v[202:205], v[94:97]
	v_mfma_i32_16x16x64_i8 v[138:141], v[160:163], v[202:205], v[138:141]
	v_mfma_i32_16x16x64_i8 v[130:133], v[98:101], v[212:215], v[130:133]
	v_mfma_i32_16x16x64_i8 v[122:125], v[160:163], v[212:215], v[122:125]
	v_mfma_i32_16x16x64_i8 v[110:113], v[98:101], v[220:223], v[110:113]
	v_mfma_i32_16x16x64_i8 v[106:109], v[160:163], v[220:223], v[106:109]
	v_mfma_i32_16x16x64_i8 v[82:85], v[98:101], v[228:231], v[82:85]
	v_mfma_i32_16x16x64_i8 v[74:77], v[160:163], v[228:231], v[74:77]
	v_mfma_i32_16x16x64_i8 v[134:137], v[182:185], v[198:201], 0
	v_mfma_i32_16x16x64_i8 v[126:129], v[190:193], v[198:201], 0
	v_mfma_i32_16x16x64_i8 v[118:121], v[182:185], v[208:211], 0
	v_mfma_i32_16x16x64_i8 v[114:117], v[190:193], v[208:211], 0
	v_mfma_i32_16x16x64_i8 v[86:89], v[182:185], v[216:219], 0
	v_mfma_i32_16x16x64_i8 v[78:81], v[190:193], v[216:219], 0
	v_mfma_i32_16x16x64_i8 v[70:73], v[182:185], v[224:227], 0
	v_mfma_i32_16x16x64_i8 v[66:69], v[190:193], v[224:227], 0
	v_mfma_i32_16x16x64_i8 v[134:137], v[186:189], v[202:205], v[134:137]
	v_mfma_i32_16x16x64_i8 v[126:129], v[194:197], v[202:205], v[126:129]
	v_mfma_i32_16x16x64_i8 v[118:121], v[186:189], v[212:215], v[118:121]
	v_mfma_i32_16x16x64_i8 v[114:117], v[194:197], v[212:215], v[114:117]
	v_mfma_i32_16x16x64_i8 v[86:89], v[186:189], v[220:223], v[86:89]
	v_mfma_i32_16x16x64_i8 v[78:81], v[194:197], v[220:223], v[78:81]
	v_mfma_i32_16x16x64_i8 v[70:73], v[186:189], v[228:231], v[70:73]
	v_mfma_i32_16x16x64_i8 v[66:69], v[194:197], v[228:231], v[66:69]
	s_barrier
	s_add_i32 s63, s14, s46
	v_lshl_add_u64 v[152:153], s[38:39], 0, v[144:145]
	s_mov_b32 m0, s63
	ds_read_b128 v[198:201], v207 offset:16384
	ds_read_b128 v[202:205], v207 offset:17408
	ds_read_b128 v[208:211], v207 offset:18432
	ds_read_b128 v[212:215], v207 offset:19456
	ds_read_b128 v[216:219], v207 offset:20480
	ds_read_b128 v[220:223], v207 offset:21504
	ds_read_b128 v[224:227], v207 offset:22528
	ds_read_b128 v[228:231], v207 offset:23552
	global_load_lds_dwordx4 v[152:153], off
	s_add_i32 m0, s63, 0x2000
	s_add_u32 s64, s38, 0x180000
	v_lshl_add_u64 v[156:157], s[38:39], 0, v[142:143]
	s_addc_u32 s65, s39, 0
	s_add_i32 s63, s55, s46
	global_load_lds_dwordx4 v[156:157], off
	v_lshl_add_u64 v[166:167], s[64:65], 0, v[144:145]
	s_mov_b32 m0, s63
	v_lshl_add_u64 v[170:171], s[40:41], 0, v[142:143]
	global_load_lds_dwordx4 v[166:167], off
	v_lshl_add_u64 v[166:167], s[64:65], 0, v[142:143]
	s_add_i32 m0, s63, 0x2000
	s_nop 0
	global_load_lds_dwordx4 v[166:167], off
	v_lshl_add_u64 v[166:167], s[40:41], 0, v[144:145]
	s_mov_b32 m0, s33
	s_nop 0
	global_load_lds_dwordx4 v[166:167], off
	s_mov_b32 m0, s49
	s_nop 0
	global_load_lds_dwordx4 v[170:171], off
	s_waitcnt vmcnt(8)
	s_waitcnt lgkmcnt(0)
	s_barrier
	s_waitcnt lgkmcnt(0)
	v_mfma_i32_16x16x64_i8 v[62:65], v[90:93], v[198:201], 0
	v_mfma_i32_16x16x64_i8 v[58:61], v[102:105], v[198:201], 0
	v_mfma_i32_16x16x64_i8 v[50:53], v[90:93], v[208:211], 0
	v_mfma_i32_16x16x64_i8 v[42:45], v[102:105], v[208:211], 0
	v_mfma_i32_16x16x64_i8 v[30:33], v[90:93], v[216:219], 0
	v_mfma_i32_16x16x64_i8 v[26:29], v[102:105], v[216:219], 0
	v_mfma_i32_16x16x64_i8 v[18:21], v[90:93], v[224:227], 0
	v_mfma_i32_16x16x64_i8 v[10:13], v[102:105], v[224:227], 0
	v_mfma_i32_16x16x64_i8 v[62:65], v[98:101], v[202:205], v[62:65]
	v_mfma_i32_16x16x64_i8 v[58:61], v[160:163], v[202:205], v[58:61]
	v_mfma_i32_16x16x64_i8 v[50:53], v[98:101], v[212:215], v[50:53]
	v_mfma_i32_16x16x64_i8 v[42:45], v[160:163], v[212:215], v[42:45]
	v_mfma_i32_16x16x64_i8 v[30:33], v[98:101], v[220:223], v[30:33]
	v_mfma_i32_16x16x64_i8 v[26:29], v[160:163], v[220:223], v[26:29]
	v_mfma_i32_16x16x64_i8 v[18:21], v[98:101], v[228:231], v[18:21]
	v_mfma_i32_16x16x64_i8 v[10:13], v[160:163], v[228:231], v[10:13]
	v_mfma_i32_16x16x64_i8 v[54:57], v[182:185], v[198:201], 0
	v_mfma_i32_16x16x64_i8 v[46:49], v[190:193], v[198:201], 0
	v_mfma_i32_16x16x64_i8 v[38:41], v[182:185], v[208:211], 0
	v_mfma_i32_16x16x64_i8 v[34:37], v[190:193], v[208:211], 0
	v_mfma_i32_16x16x64_i8 v[22:25], v[182:185], v[216:219], 0
	v_mfma_i32_16x16x64_i8 v[14:17], v[190:193], v[216:219], 0
	v_mfma_i32_16x16x64_i8 v[6:9], v[182:185], v[224:227], 0
	v_mfma_i32_16x16x64_i8 v[2:5], v[190:193], v[224:227], 0
	v_mfma_i32_16x16x64_i8 v[54:57], v[186:189], v[202:205], v[54:57]
	v_mfma_i32_16x16x64_i8 v[46:49], v[194:197], v[202:205], v[46:49]
	v_mfma_i32_16x16x64_i8 v[38:41], v[186:189], v[212:215], v[38:41]
	v_mfma_i32_16x16x64_i8 v[34:37], v[194:197], v[212:215], v[34:37]
	v_mfma_i32_16x16x64_i8 v[22:25], v[186:189], v[220:223], v[22:25]
	v_mfma_i32_16x16x64_i8 v[14:17], v[194:197], v[220:223], v[14:17]
	v_mfma_i32_16x16x64_i8 v[6:9], v[186:189], v[228:231], v[6:9]
	v_mfma_i32_16x16x64_i8 v[2:5], v[194:197], v[228:231], v[2:5]
	s_barrier
; #define PG8_STAGE(bufoff, gbase, voff) do { _Pragma("unroll") for (int _i = 0; _i < 2; ++_i) \
;         __builtin_amdgcn_global_load_lds((const unsigned*)((const char*)(gbase) + (voff)[_i]), (LAS unsigned*)(lds + (bufoff) + ldsw + _i * 8192), 16, 0, 0); } while (0)
; #define PG8_LDA(dst, b, h) do { _Pragma("unroll") for (int m = 0; m < 4; ++m) _Pragma("unroll") for (int k = 0; k < 2; ++k) dst[m][k] = *(const LAS bf16x8*)(lds + PG8_SA(b, h) + aoff + m * 2048 + k * 1024); } while (0)
; #define PG8_LDB(dst, b, h) do { _Pragma("unroll") for (int n = 0; n < 2; ++n) _Pragma("unroll") for (int k = 0; k < 2; ++k) dst[n][k] = *(const LAS bf16x8*)(lds + PG8_SB(b, h) + boff + n * 2048 + k * 1024); } while (0)
; #define PG8_WAIT_V(n) asm volatile("s_waitcnt vmcnt(" #n ")" ::: "memory")
; #define PG8_WAIT_L(n) asm volatile("s_waitcnt lgkmcnt(" #n ")" ::: "memory")
; #define PG8_BAR __builtin_amdgcn_s_barrier()
; #define PG8_SCHED __builtin_amdgcn_sched_barrier(0)
; template <class Epi, class Geom, class Sched, bool ALIGN_EPI, bool I8 = false>
; __device__ __forceinline__ void gemm_phase(LAS unsigned char* lds, const Gemm g, const Sched& S, const Epi& E) {
;     ...
;             PG8_LDB(B0, 1, 0); PG8_LDB(B1, 1, 1); PG8_SCHED; PG8_LDA(At, 1, 0); PG8_STAGE(PG8_SA(0, 1), a2 + hsA, voffA);
;             PG8_WAIT_V(8); PG8_WAIT_L(0); PG8_BAR; PG8_MMA(0, 0, At, B0); PG8_MMA(0, 1, At, B1); PG8_BAR; PG8_SCHED;
;             PG8_LDA(At, 1, 1); PG8_STAGE(PG8_SB(1, 0), b3, voffB); PG8_STAGE(PG8_SB(1, 1), b3 + hsB, voffB); PG8_STAGE(PG8_SA(1, 0), a3, voffA);
;             PG8_WAIT_V(8); PG8_WAIT_L(0); PG8_BAR; PG8_MMA(1, 0, At, B0); PG8_MMA(1, 1, At, B1); PG8_BAR; PG8_SCHED;
;         }
	s_add_i32 s63, 0, 0x18000
	v_add_u32_e32 v154, s63, v175
	s_add_i32 s64, 0, 0x1c000
	ds_read_b128 v[90:93], v154
	ds_read_b128 v[98:101], v154 offset:1024
	ds_read_b128 v[102:105], v154 offset:2048
	ds_read_b128 v[160:163], v154 offset:3072
	v_add_u32_e32 v154, s64, v175
	ds_read_b128 v[182:185], v154
	ds_read_b128 v[186:189], v154 offset:1024
	ds_read_b128 v[190:193], v154 offset:2048
	ds_read_b128 v[194:197], v154 offset:3072
	s_add_u32 s40, s40, 0x180000
	s_addc_u32 s41, s41, 0
	s_mov_b32 m0, s50
	v_lshl_add_u64 v[176:177], s[40:41], 0, v[144:145]
	ds_read_b128 v[198:201], v207 offset:32768
	ds_read_b128 v[202:205], v207 offset:33792
	ds_read_b128 v[208:211], v207 offset:34816
	ds_read_b128 v[212:215], v207 offset:35840
	ds_read_b128 v[216:219], v207 offset:36864
	ds_read_b128 v[220:223], v207 offset:37888
	ds_read_b128 v[224:227], v207 offset:38912
	ds_read_b128 v[228:231], v207 offset:39936
	global_load_lds_dwordx4 v[176:177], off
	v_lshl_add_u64 v[176:177], s[40:41], 0, v[142:143]
	s_mov_b32 m0, s51
	s_nop 0
	global_load_lds_dwordx4 v[176:177], off
	s_waitcnt vmcnt(8)
	s_waitcnt lgkmcnt(0)
	s_barrier
	s_waitcnt lgkmcnt(0)
	v_mfma_i32_16x16x64_i8 v[94:97], v[90:93], v[198:201], v[94:97]
	v_mfma_i32_16x16x64_i8 v[138:141], v[102:105], v[198:201], v[138:141]
	v_mfma_i32_16x16x64_i8 v[130:133], v[90:93], v[208:211], v[130:133]
	v_mfma_i32_16x16x64_i8 v[122:125], v[102:105], v[208:211], v[122:125]
	v_mfma_i32_16x16x64_i8 v[110:113], v[90:93], v[216:219], v[110:113]
	v_mfma_i32_16x16x64_i8 v[106:109], v[102:105], v[216:219], v[106:109]
	v_mfma_i32_16x16x64_i8 v[82:85], v[90:93], v[224:227], v[82:85]
	v_mfma_i32_16x16x64_i8 v[74:77], v[102:105], v[224:227], v[74:77]
	v_mfma_i32_16x16x64_i8 v[94:97], v[98:101], v[202:205], v[94:97]
	v_mfma_i32_16x16x64_i8 v[138:141], v[160:163], v[202:205], v[138:141]
	v_mfma_i32_16x16x64_i8 v[130:133], v[98:101], v[212:215], v[130:133]
	v_mfma_i32_16x16x64_i8 v[122:125], v[160:163], v[212:215], v[122:125]
	v_mfma_i32_16x16x64_i8 v[110:113], v[98:101], v[220:223], v[110:113]
	v_mfma_i32_16x16x64_i8 v[106:109], v[160:163], v[220:223], v[106:109]
	v_mfma_i32_16x16x64_i8 v[82:85], v[98:101], v[228:231], v[82:85]
	v_mfma_i32_16x16x64_i8 v[74:77], v[160:163], v[228:231], v[74:77]
	v_mfma_i32_16x16x64_i8 v[134:137], v[182:185], v[198:201], v[134:137]
	v_mfma_i32_16x16x64_i8 v[126:129], v[190:193], v[198:201], v[126:129]
	v_mfma_i32_16x16x64_i8 v[118:121], v[182:185], v[208:211], v[118:121]
	v_mfma_i32_16x16x64_i8 v[114:117], v[190:193], v[208:211], v[114:117]
	v_mfma_i32_16x16x64_i8 v[86:89], v[182:185], v[216:219], v[86:89]
	v_mfma_i32_16x16x64_i8 v[78:81], v[190:193], v[216:219], v[78:81]
	v_mfma_i32_16x16x64_i8 v[70:73], v[182:185], v[224:227], v[70:73]
	v_mfma_i32_16x16x64_i8 v[66:69], v[190:193], v[224:227], v[66:69]
	v_mfma_i32_16x16x64_i8 v[134:137], v[186:189], v[202:205], v[134:137]
	v_mfma_i32_16x16x64_i8 v[126:129], v[194:197], v[202:205], v[126:129]
	v_mfma_i32_16x16x64_i8 v[118:121], v[186:189], v[212:215], v[118:121]
	v_mfma_i32_16x16x64_i8 v[114:117], v[194:197], v[212:215], v[114:117]
	v_mfma_i32_16x16x64_i8 v[86:89], v[186:189], v[220:223], v[86:89]
	v_mfma_i32_16x16x64_i8 v[78:81], v[194:197], v[220:223], v[78:81]
	v_mfma_i32_16x16x64_i8 v[70:73], v[186:189], v[228:231], v[70:73]
	v_mfma_i32_16x16x64_i8 v[66:69], v[194:197], v[228:231], v[66:69]
	s_barrier
	s_add_i32 s40, s63, s46
	v_lshl_add_u64 v[152:153], v[152:153], 0, s[20:21]
	s_mov_b32 m0, s40
	ds_read_b128 v[198:201], v207 offset:49152
	ds_read_b128 v[202:205], v207 offset:50176
	ds_read_b128 v[208:211], v207 offset:51200
	ds_read_b128 v[212:215], v207 offset:52224
	ds_read_b128 v[216:219], v207 offset:53248
	ds_read_b128 v[220:223], v207 offset:54272
	ds_read_b128 v[224:227], v207 offset:55296
	ds_read_b128 v[228:231], v207 offset:56320
	global_load_lds_dwordx4 v[152:153], off
	s_add_i32 m0, s40, 0x2000
	s_add_u32 s38, s38, 0x180080
	v_lshl_add_u64 v[152:153], v[156:157], 0, s[20:21]
	s_addc_u32 s39, s39, 0
	s_add_i32 s40, s64, s46
	global_load_lds_dwordx4 v[152:153], off
	v_lshl_add_u64 v[152:153], s[38:39], 0, v[144:145]
	s_mov_b32 m0, s40
	s_nop 0
	global_load_lds_dwordx4 v[152:153], off
	v_lshl_add_u64 v[152:153], s[38:39], 0, v[142:143]
	s_add_i32 m0, s40, 0x2000
	s_nop 0
	global_load_lds_dwordx4 v[152:153], off
	v_lshl_add_u64 v[152:153], v[166:167], 0, s[20:21]
	s_mov_b32 m0, s52
	s_nop 0
	global_load_lds_dwordx4 v[152:153], off
	v_lshl_add_u64 v[152:153], v[170:171], 0, s[20:21]
	s_mov_b32 m0, s53
	s_nop 0
	global_load_lds_dwordx4 v[152:153], off
	s_waitcnt vmcnt(8)
	s_waitcnt lgkmcnt(0)
	s_barrier
	s_waitcnt lgkmcnt(0)
	v_mfma_i32_16x16x64_i8 v[62:65], v[90:93], v[198:201], v[62:65]
	v_mfma_i32_16x16x64_i8 v[58:61], v[102:105], v[198:201], v[58:61]
	v_mfma_i32_16x16x64_i8 v[50:53], v[90:93], v[208:211], v[50:53]
	v_mfma_i32_16x16x64_i8 v[42:45], v[102:105], v[208:211], v[42:45]
	v_mfma_i32_16x16x64_i8 v[30:33], v[90:93], v[216:219], v[30:33]
	v_mfma_i32_16x16x64_i8 v[26:29], v[102:105], v[216:219], v[26:29]
	v_mfma_i32_16x16x64_i8 v[18:21], v[90:93], v[224:227], v[18:21]
	v_mfma_i32_16x16x64_i8 v[10:13], v[102:105], v[224:227], v[10:13]
	v_mfma_i32_16x16x64_i8 v[62:65], v[98:101], v[202:205], v[62:65]
	v_mfma_i32_16x16x64_i8 v[58:61], v[160:163], v[202:205], v[58:61]
	v_mfma_i32_16x16x64_i8 v[50:53], v[98:101], v[212:215], v[50:53]
	v_mfma_i32_16x16x64_i8 v[42:45], v[160:163], v[212:215], v[42:45]
	v_mfma_i32_16x16x64_i8 v[30:33], v[98:101], v[220:223], v[30:33]
	v_mfma_i32_16x16x64_i8 v[26:29], v[160:163], v[220:223], v[26:29]
	v_mfma_i32_16x16x64_i8 v[18:21], v[98:101], v[228:231], v[18:21]
	v_mfma_i32_16x16x64_i8 v[10:13], v[160:163], v[228:231], v[10:13]
	v_mfma_i32_16x16x64_i8 v[54:57], v[182:185], v[198:201], v[54:57]
	v_mfma_i32_16x16x64_i8 v[46:49], v[190:193], v[198:201], v[46:49]
	v_mfma_i32_16x16x64_i8 v[38:41], v[182:185], v[208:211], v[38:41]
	v_mfma_i32_16x16x64_i8 v[34:37], v[190:193], v[208:211], v[34:37]
	v_mfma_i32_16x16x64_i8 v[22:25], v[182:185], v[216:219], v[22:25]
	v_mfma_i32_16x16x64_i8 v[14:17], v[190:193], v[216:219], v[14:17]
	v_mfma_i32_16x16x64_i8 v[6:9], v[182:185], v[224:227], v[6:9]
	v_mfma_i32_16x16x64_i8 v[2:5], v[190:193], v[224:227], v[2:5]
	v_mfma_i32_16x16x64_i8 v[54:57], v[186:189], v[202:205], v[54:57]
	v_mfma_i32_16x16x64_i8 v[46:49], v[194:197], v[202:205], v[46:49]
	v_mfma_i32_16x16x64_i8 v[38:41], v[186:189], v[212:215], v[38:41]
	v_mfma_i32_16x16x64_i8 v[34:37], v[194:197], v[212:215], v[34:37]
	v_mfma_i32_16x16x64_i8 v[22:25], v[186:189], v[220:223], v[22:25]
	v_mfma_i32_16x16x64_i8 v[14:17], v[194:197], v[220:223], v[14:17]
	v_mfma_i32_16x16x64_i8 v[6:9], v[186:189], v[228:231], v[6:9]
	v_mfma_i32_16x16x64_i8 v[2:5], v[194:197], v[228:231], v[2:5]
	s_barrier
	s_add_i32 s62, s62, 2
	s_add_u32 s36, s36, 0x100
	s_addc_u32 s37, s37, 0
	s_add_u32 s60, s60, 0x100
	s_addc_u32 s61, s61, 0
	s_cmpk_gt_u32 s62, 0x5d
	s_branch .LBB0_2872
